# MLA loops: one static s_setprio 1 for waves 4-7 (younger half) before the loop, reset at loop exit
# speedup vs baseline: 1.0122x; 1.0030x over previous
; DI int opaque_tid() { int t = threadIdx.x; asm volatile("" : "+v"(t)); return t; }
;     DI const bf16_t* Q() const { return (const bf16_t*)(ws + WS_Q); }
;     DI const bf16_t* KV() const { return (const bf16_t*)(ws + WS_KV); }
;     DI const bf16_t* KPE() const { return (const bf16_t*)(ws + WS_KPE); }
; #define MLA_LOAD() do { sreg[0] = *(const u32x4*)(kp0); sreg[1] = *(const u32x4*)(kp0 + 64); sreg[2] = *(const u32x4*)(kp0 + 128); sreg[3] = *(const u32x4*)(kp0 + 192); \
;         sreg[4] = *(const u32x4*)(kp1); kp0 += (size_t)64 * 2048; kp1 += (size_t)64 * 64; } while (0)
; #define MLA_WRITE(buf) do { LAS unsigned char* kd_ = lds + (buf) * BUFB + lkey * KSTR + lq * 16; LAS unsigned char* vd_ = lds + (buf) * BUFB + 64 * KSTR + lkey * VSTR + lq * 16; \
;         *(LAS u32x4*)(kd_) = sreg[0]; *(LAS u32x4*)(kd_ + 128) = sreg[1]; *(LAS u32x4*)(kd_ + 256) = sreg[4]; *(LAS u32x4*)(vd_) = sreg[2]; *(LAS u32x4*)(vd_ + 128) = sreg[3]; } while (0)
; template <bool ATOM>
; DI void mla_unit(LAS unsigned char* lds, const AttnPtrs& P, int b, int hd, int qb) {
;     ...
;     const int tid = opaque_tid(), lane = tid & 63, wid = __builtin_amdgcn_readfirstlane(tid >> 6), r = lane & 31, h = lane >> 5, rg = wid & 3, kh = wid >> 2;
;     const int fq_ = qb * 128 + rg * 32 + r;
;     const size_t tokq = (size_t)b * 2048 + fq_;
;     bf16x8 qf[NKK];
;     { const bf16_t* qp = P.Q() + tokq * 1536 + hd * 192;
; #pragma unroll
;       for (int kk = 0; kk < NKK; ++kk) qf[kk] = *(const bf16x8*)(qp + kk * 16 + 8 * h); }
;     f32x16 o[NDV];
; #pragma unroll
;     for (int d = 0; d < NDV; ++d)
; #pragma unroll
;         for (int i = 0; i < 16; ++i) o[d][i] = 0.f;
;     float mrun = -INFINITY, lrun = 0.f;
;     const int lkey = tid >> 3, lq = tid & 7;
;     const bf16_t* kp0 = P.KV() + ((size_t)b * 2048 + lkey) * 2048 + hd * 256 + lq * 8;
;     const bf16_t* kp1 = P.KPE() + ((size_t)b * 2048 + lkey) * 64 + lq * 8;
;     u32x4 sreg[5];
;     ...
;     const int nsteps = 2 * (qb + 1);
;     __syncthreads();
;     MLA_LOAD(); MLA_WRITE(0);
;     MLA_LOAD();
;     __syncthreads();
;     const int kwo = (kh * 32 + r) * KSTR + h * 16;
;     const int vwo = 64 * KSTR + (kh * 32 + 4 * h + ((lane & 15) >> 2)) * VSTR + (16 * ((lane >> 4) & 1) + 4 * (lane & 3)) * 2;
;     for (int t = 0; t < nsteps; ++t) {
.LBB0_1048:
	s_and_b64 s[14:15], s[8:9], exec
	v_mov_b32_e32 v30, v188
	s_cselect_b32 s4, s1, s0
	s_and_b32 s16, s4, 7
	v_readfirstlane_b32 s18, v30
	s_bfe_u32 s19, s18, 0x20006
	s_ashr_i32 s14, s4, 6
	s_lshl_b32 s23, s16, 7
	s_lshl_b32 s15, s19, 5
	v_and_b32_e32 v31, 31, v30
	s_or_b32 s34, s15, s23
	s_ashr_i32 s15, s14, 31
	v_or_b32_e32 v214, s34, v31
	s_lshl_b64 s[50:51], s[14:15], 11
	s_bfe_u32 s4, s4, 0x30003
	v_or_b32_e32 v130, s50, v214
	s_waitcnt lgkmcnt(0)
	v_mov_b64_e32 v[0:1], s[10:11]
	v_mad_u64_u32 v[0:1], s[14:15], v130, s90, v[0:1]
	s_mul_i32 s17, s4, 0xc0
	v_bfe_u32 v32, v30, 5, 1
	v_mad_i32_i24 v1, s51, v207, v1
	s_lshl_b32 s38, s17, 1
	v_lshl_add_u64 v[0:1], v[0:1], 0, s[38:39]
	v_lshlrev_b32_e32 v128, 4, v32
	v_ashrrev_i32_e32 v20, 3, v30
	v_lshl_add_u64 v[0:1], v[0:1], 0, v[128:129]
	v_ashrrev_i32_e32 v21, 31, v20
	global_load_dwordx4 v[180:183], v[0:1], off
	global_load_dwordx4 v[176:179], v[0:1], off offset:32
	global_load_dwordx4 v[172:175], v[0:1], off offset:64
	global_load_dwordx4 v[168:171], v[0:1], off offset:96
	global_load_dwordx4 v[164:167], v[0:1], off offset:128
	global_load_dwordx4 v[160:163], v[0:1], off offset:160
	global_load_dwordx4 v[156:159], v[0:1], off offset:192
	global_load_dwordx4 v[152:155], v[0:1], off offset:224
	global_load_dwordx4 v[148:151], v[0:1], off offset:256
	global_load_dwordx4 v[144:147], v[0:1], off offset:288
	global_load_dwordx4 v[140:143], v[0:1], off offset:320
	global_load_dwordx4 v[136:139], v[0:1], off offset:352
	v_lshl_add_u64 v[0:1], s[50:51], 0, v[20:21]
	v_lshlrev_b64 v[2:3], 12, v[0:1]
	v_lshlrev_b32_e32 v4, 4, v30
	v_lshlrev_b64 v[0:1], 7, v[0:1]
	v_lshl_add_u64 v[2:3], s[12:13], 0, v[2:3]
	s_lshl_b32 s38, s4, 9
	v_and_b32_e32 v116, 0x70, v4
	v_mov_b32_e32 v117, v129
	v_lshl_add_u64 v[0:1], s[42:43], 0, v[0:1]
	v_lshl_add_u64 v[2:3], v[2:3], 0, s[38:39]
	v_lshl_add_u64 v[24:25], v[0:1], 0, v[116:117]
	v_lshl_add_u64 v[22:23], v[2:3], 0, v[116:117]
	s_barrier
	global_load_dwordx4 v[0:3], v[24:25], off
	global_load_dwordx4 v[4:7], v[22:23], off
	global_load_dwordx4 v[8:11], v[22:23], off offset:128
	global_load_dwordx4 v[12:15], v[22:23], off offset:256
	global_load_dwordx4 v[16:19], v[22:23], off offset:384
	v_add_co_u32_e32 v26, vcc, s89, v22
	s_movk_i32 s14, 0x2000
	s_nop 0
	v_addc_co_u32_e32 v27, vcc, 0, v23, vcc
	global_load_dwordx4 v[96:99], v[26:27], off
	global_load_dwordx4 v[100:103], v[26:27], off offset:128
	global_load_dwordx4 v[104:107], v[26:27], off offset:256
	v_add_co_u32_e32 v28, vcc, s14, v24
	s_lshl_b32 s48, s4, 8
	s_nop 0
	v_addc_co_u32_e32 v29, vcc, 0, v25, vcc
	global_load_dwordx4 v[108:111], v[26:27], off offset:384
	global_load_dwordx4 v[112:115], v[28:29], off
	s_movk_i32 s4, 0x190
	v_mul_lo_u32 v117, v20, s4
	s_ashr_i32 s22, s18, 8
	s_movk_i32 s38, 0x120
	v_add3_u32 v26, 0, v117, v116
	s_movk_i32 s35, 0xff90
	v_mul_lo_u32 v122, v20, s38
	v_mad_u64_u32 v[20:21], s[36:37], v20, s35, v[26:27]
	s_lshl_b32 s35, s22, 5
	v_lshlrev_b32_e32 v209, 2, v32
	s_mov_b64 s[36:37], 0x4000
	v_and_b32_e32 v208, 63, v30
	v_lshl_add_u64 v[118:119], v[24:25], 0, s[36:37]
	s_mov_b64 s[36:37], 0x80000
	v_lshl_add_u64 v[120:121], v[22:23], 0, s[36:37]
	v_mov_b32_e32 v21, v129
	v_mov_b32_e32 v22, v129
	v_mov_b32_e32 v23, v129
	v_mov_b32_e32 v24, v129
	v_mov_b32_e32 v25, v129
	v_mov_b32_e32 v27, v129
	v_mov_b32_e32 v28, v129
	v_mov_b32_e32 v29, v129
	s_mov_b32 s14, 0
	s_lshl_b32 s15, s16, 1
	v_mov_b32_e32 v131, s51
	s_or_b32 s36, s34, 31
	s_or_b32 s37, s23, 64
	v_or_b32_e32 v123, s35, v209
	v_mov_b32_e32 v213, 0
	v_mov_b32_e32 v124, 0xff800000
	s_waitcnt vmcnt(9)
	ds_write_b128 v26, v[0:3] offset:256
	s_waitcnt vmcnt(8)
	ds_write_b128 v26, v[4:7]
	s_waitcnt vmcnt(7)
	ds_write_b128 v26, v[8:11] offset:128
	s_waitcnt vmcnt(6)
	ds_write_b128 v20, v[12:15] offset:25600
	s_waitcnt vmcnt(5)
	ds_write_b128 v20, v[16:19] offset:25728
	v_or_b32_e32 v0, s35, v31
	v_mul_lo_u32 v215, v0, s4
	v_bfe_u32 v0, v30, 2, 2
	v_or3_b32 v0, v209, v0, s35
	v_mul_lo_u32 v210, v0, s38
	v_and_b32_e32 v0, 16, v30
	v_lshlrev_b32_e32 v1, 2, v30
	v_mov_b32_e32 v30, v129
	v_mov_b32_e32 v31, v129
	v_and_or_b32 v0, v1, 12, v0
	v_mov_b32_e32 v16, v129
	v_mov_b32_e32 v17, v129
	v_mov_b32_e32 v18, v129
	v_mov_b32_e32 v19, v129
	v_mov_b32_e32 v20, v129
	v_mov_b32_e32 v26, v129
	v_mov_b64_e32 v[46:47], v[30:31]
	v_mov_b64_e32 v[62:63], v[30:31]
	v_mov_b64_e32 v[78:79], v[30:31]
	v_lshlrev_b32_e32 v211, 1, v0
	v_mov_b64_e32 v[44:45], v[28:29]
	v_mov_b64_e32 v[42:43], v[26:27]
	v_mov_b64_e32 v[40:41], v[24:25]
	v_mov_b64_e32 v[38:39], v[22:23]
	v_mov_b64_e32 v[36:37], v[20:21]
	v_mov_b64_e32 v[34:35], v[18:19]
	v_mov_b64_e32 v[32:33], v[16:17]
	v_mov_b64_e32 v[60:61], v[28:29]
	v_mov_b64_e32 v[58:59], v[26:27]
	v_mov_b64_e32 v[56:57], v[24:25]
	v_mov_b64_e32 v[54:55], v[22:23]
	v_mov_b64_e32 v[52:53], v[20:21]
	v_mov_b64_e32 v[50:51], v[18:19]
	v_mov_b64_e32 v[48:49], v[16:17]
	v_mov_b64_e32 v[76:77], v[28:29]
	v_mov_b64_e32 v[74:75], v[26:27]
	v_mov_b64_e32 v[72:73], v[24:25]
	v_mov_b64_e32 v[70:71], v[22:23]
	v_mov_b64_e32 v[68:69], v[20:21]
	v_mov_b64_e32 v[66:67], v[18:19]
	v_mov_b64_e32 v[64:65], v[16:17]
	s_mov_b32 s4, 0
	s_waitcnt lgkmcnt(0)
	s_barrier
	s_cmp_lg_u32 s35, 0
	s_cbranch_scc0 .Lprio_skip_1
	s_setprio 1
.Lprio_skip_1:
.LBB0_1049:
	s_add_i32 s38, s4, 1
	s_bitcmp1_b32 s38, 0
	s_cselect_b32 s23, 0xac00, 0
	s_add_i32 s23, s23, 0
	v_add3_u32 v0, s23, v117, v116
	v_add3_u32 v1, s23, v122, v116
	s_cmp_ge_u32 s4, s15
	s_waitcnt vmcnt(4)
	ds_write_b128 v0, v[96:99]
	s_waitcnt vmcnt(3)
	ds_write_b128 v0, v[100:103] offset:128
	s_waitcnt vmcnt(0)
	ds_write_b128 v0, v[112:115] offset:256
	ds_write_b128 v1, v[104:107] offset:25600
	ds_write_b128 v1, v[108:111] offset:25728
	s_cbranch_scc1 .LBB0_1051
	global_load_dwordx4 v[96:99], v[120:121], off
	global_load_dwordx4 v[100:103], v[120:121], off offset:128
	global_load_dwordx4 v[104:107], v[120:121], off offset:256
	global_load_dwordx4 v[108:111], v[120:121], off offset:384
	global_load_dwordx4 v[112:115], v[118:119], off
	v_lshl_add_u64 v[120:121], v[120:121], 0, s[20:21]
	v_lshl_add_u64 v[118:119], v[118:119], 0, s[24:25]

; #define LAS __attribute__((address_space(3)))
; DI int crow(int i, int h) { return (i & 3) + 8 * (i >> 2) + 4 * h; }
; #define MFMA32(a, b, c) __builtin_amdgcn_mfma_f32_32x32x16_bf16((a), (b), (c), 0, 0, 0)
; template <bool ATOM>
; DI void mla_unit(LAS unsigned char* lds, const AttnPtrs& P, int b, int hd, int qb) {
;     ...
;         const int keyb = t * 64 + kh * 32;
;         if (keyb <= qb * 128 + rg * 32 + 31) {
;             const LAS unsigned char* Kw = lds + (t & 1) * BUFB + kwo;
;             const LAS unsigned char* Vw = lds + (t & 1) * BUFB + vwo;
;             f32x16 xa, xb;
; #pragma unroll
;             for (int i = 0; i < 16; ++i) { xa[i] = 0.f; xb[i] = 0.f; }
; #pragma unroll
;             for (int kk = 0; kk < NKK; kk += 2) {
;                 const bf16x8 a0 = *(const LAS bf16x8*)(Kw + kk * 32), a1 = *(const LAS bf16x8*)(Kw + kk * 32 + 32);
;                 xa = MFMA32(a0, qf[kk], xa); xb = MFMA32(a1, qf[kk + 1], xb);
;                 if ((kk & 3) == 2) __builtin_amdgcn_sched_barrier(0);
;             }
;             f32x16 x0;
; #pragma unroll
;             for (int i = 0; i < 16; ++i) x0[i] = xa[i] + xb[i];
;             if (keyb + 31 > qb * 128 + rg * 32) {
; #pragma unroll
;                 for (int i = 0; i < 16; ++i) if (keyb + crow(i, h) > fq_) x0[i] = -INFINITY;
;             }
;             float mloc = x0[0];
; #pragma unroll
;             for (int i = 1; i < 16; ++i) mloc = fmaxf(mloc, x0[i]);
;             mloc = fmaxf(mloc, __shfl_xor(mloc, 32));
.LBB0_1060:
	s_setprio 0
	s_lshl_b32 s4, s38, 6
	s_add_i32 s4, s4, s35
	s_cmp_le_i32 s4, s36
	s_mov_b64 s[14:15], -1
	s_cbranch_scc0 .LBB0_1066
	s_waitcnt vmcnt(2)
	v_add3_u32 v104, s23, v215, v128
	ds_read_b128 v[0:3], v104
	ds_read_b128 v[80:83], v104 offset:32
	ds_read_b128 v[96:99], v104 offset:64
	ds_read_b128 v[100:103], v104 offset:96
	s_waitcnt lgkmcnt(3)
	v_mfma_f32_32x32x16_bf16 v[0:15], v[0:3], v[180:183], 0
	s_waitcnt lgkmcnt(2)
	v_mfma_f32_32x32x16_bf16 v[80:95], v[80:83], v[176:179], 0
	s_waitcnt lgkmcnt(1)
	v_mfma_f32_32x32x16_bf16 v[0:15], v[96:99], v[172:175], v[0:15]
	s_waitcnt lgkmcnt(0)
	v_mfma_f32_32x32x16_bf16 v[80:95], v[100:103], v[168:171], v[80:95]
	ds_read_b128 v[96:99], v104 offset:128
	s_waitcnt lgkmcnt(0)
	v_mfma_f32_32x32x16_bf16 v[0:15], v[96:99], v[164:167], v[0:15]
	ds_read_b128 v[96:99], v104 offset:160
	s_waitcnt lgkmcnt(0)
	v_mfma_f32_32x32x16_bf16 v[80:95], v[96:99], v[160:163], v[80:95]
	ds_read_b128 v[96:99], v104 offset:192
	s_waitcnt lgkmcnt(0)
	v_mfma_f32_32x32x16_bf16 v[0:15], v[96:99], v[156:159], v[0:15]
	ds_read_b128 v[96:99], v104 offset:224
	s_waitcnt lgkmcnt(0)
	v_mfma_f32_32x32x16_bf16 v[80:95], v[96:99], v[152:155], v[80:95]
	ds_read_b128 v[96:99], v104 offset:256
	s_waitcnt lgkmcnt(0)
	v_mfma_f32_32x32x16_bf16 v[0:15], v[96:99], v[148:151], v[0:15]
	ds_read_b128 v[96:99], v104 offset:288
	s_waitcnt lgkmcnt(0)
	v_mfma_f32_32x32x16_bf16 v[80:95], v[96:99], v[144:147], v[80:95]
	ds_read_b128 v[96:99], v104 offset:320
	s_waitcnt lgkmcnt(0)
	v_mfma_f32_32x32x16_bf16 v[0:15], v[96:99], v[140:143], v[0:15]
	ds_read_b128 v[96:99], v104 offset:352
	s_waitcnt lgkmcnt(0)
	v_mfma_f32_32x32x16_bf16 v[80:95], v[96:99], v[136:139], v[80:95]
	s_or_b32 s14, s4, 31
	s_nop 10
	v_pk_add_f32 v[136:137], v[14:15], v[94:95]
	v_pk_add_f32 v[138:139], v[12:13], v[92:93]
	v_pk_add_f32 v[140:141], v[10:11], v[90:91]
	v_pk_add_f32 v[142:143], v[8:9], v[88:89]
	v_pk_add_f32 v[144:145], v[6:7], v[86:87]
	v_pk_add_f32 v[146:147], v[4:5], v[84:85]
	v_pk_add_f32 v[148:149], v[2:3], v[82:83]
	s_cmp_le_i32 s14, s34
	v_pk_add_f32 v[150:151], v[0:1], v[80:81]
	s_cbranch_scc1 .LBB0_1063
	v_or_b32_e32 v0, s4, v209
	v_cmp_lt_i32_e32 vcc, v0, v214
	v_or_b32_e32 v1, 2, v0
	s_nop 0
	v_cndmask_b32_e32 v151, v205, v151, vcc
	v_cmp_le_i32_e32 vcc, v0, v214
	s_nop 1
	v_cndmask_b32_e32 v150, v205, v150, vcc
	v_cmp_le_i32_e32 vcc, v1, v214
	v_or_b32_e32 v1, 3, v0
	s_nop 0
	v_cndmask_b32_e32 v148, v205, v148, vcc
	v_cmp_le_i32_e32 vcc, v1, v214
	v_or_b32_e32 v1, 8, v0
	s_nop 0
	v_cndmask_b32_e32 v149, v205, v149, vcc
	v_cmp_le_i32_e32 vcc, v1, v214
	v_or_b32_e32 v1, 9, v0
	s_nop 0
	v_cndmask_b32_e32 v146, v205, v146, vcc
	v_cmp_le_i32_e32 vcc, v1, v214
	v_or_b32_e32 v1, 10, v0
	s_nop 0
	v_cndmask_b32_e32 v147, v205, v147, vcc
	v_cmp_le_i32_e32 vcc, v1, v214
	v_or_b32_e32 v1, 11, v0
	s_nop 0
	v_cndmask_b32_e32 v144, v205, v144, vcc
	v_cmp_le_i32_e32 vcc, v1, v214
	v_or_b32_e32 v1, 16, v0
	s_nop 0
	v_cndmask_b32_e32 v145, v205, v145, vcc
	v_cmp_le_i32_e32 vcc, v1, v214
	v_or_b32_e32 v1, 17, v0
	s_nop 0
	v_cndmask_b32_e32 v142, v205, v142, vcc
	v_cmp_le_i32_e32 vcc, v1, v214
	v_or_b32_e32 v1, 18, v0
	s_nop 0
	v_cndmask_b32_e32 v143, v205, v143, vcc
	v_cmp_le_i32_e32 vcc, v1, v214
	v_or_b32_e32 v1, 19, v0
	s_nop 0
	v_cndmask_b32_e32 v140, v205, v140, vcc
	v_cmp_le_i32_e32 vcc, v1, v214
	v_or_b32_e32 v1, 24, v0
	s_nop 0
	v_cndmask_b32_e32 v141, v205, v141, vcc
	v_cmp_le_i32_e32 vcc, v1, v214
	v_or_b32_e32 v1, 25, v0
	s_nop 0
	v_cndmask_b32_e32 v138, v205, v138, vcc
	v_cmp_le_i32_e32 vcc, v1, v214
	v_or_b32_e32 v1, 26, v0
	v_or_b32_e32 v0, 27, v0
	v_cndmask_b32_e32 v139, v205, v139, vcc
	v_cmp_le_i32_e32 vcc, v1, v214
	s_nop 1
	v_cndmask_b32_e32 v136, v205, v136, vcc
	v_cmp_le_i32_e32 vcc, v0, v214
	s_nop 1
	v_cndmask_b32_e32 v137, v205, v137, vcc

; DI int opaque_tid() { int t = threadIdx.x; asm volatile("" : "+v"(t)); return t; }
;     DI const bf16_t* Q() const { return (const bf16_t*)(ws + WS_Q); }
;     DI const bf16_t* KV() const { return (const bf16_t*)(ws + WS_KV); }
;     DI const bf16_t* KPE() const { return (const bf16_t*)(ws + WS_KPE); }
; #define MLA_LOAD() do { sreg[0] = *(const u32x4*)(kp0); sreg[1] = *(const u32x4*)(kp0 + 64); sreg[2] = *(const u32x4*)(kp0 + 128); sreg[3] = *(const u32x4*)(kp0 + 192); \
;         sreg[4] = *(const u32x4*)(kp1); kp0 += (size_t)64 * 2048; kp1 += (size_t)64 * 64; } while (0)
; #define MLA_WRITE(buf) do { LAS unsigned char* kd_ = lds + (buf) * BUFB + lkey * KSTR + lq * 16; LAS unsigned char* vd_ = lds + (buf) * BUFB + 64 * KSTR + lkey * VSTR + lq * 16; \
;         *(LAS u32x4*)(kd_) = sreg[0]; *(LAS u32x4*)(kd_ + 128) = sreg[1]; *(LAS u32x4*)(kd_ + 256) = sreg[4]; *(LAS u32x4*)(vd_) = sreg[2]; *(LAS u32x4*)(vd_ + 128) = sreg[3]; } while (0)
; template <bool ATOM>
; DI void mla_unit(LAS unsigned char* lds, const AttnPtrs& P, int b, int hd, int qb) {
;     ...
;     const int tid = opaque_tid(), lane = tid & 63, wid = __builtin_amdgcn_readfirstlane(tid >> 6), r = lane & 31, h = lane >> 5, rg = wid & 3, kh = wid >> 2;
;     const int fq_ = qb * 128 + rg * 32 + r;
;     const size_t tokq = (size_t)b * 2048 + fq_;
;     bf16x8 qf[NKK];
;     { const bf16_t* qp = P.Q() + tokq * 1536 + hd * 192;
; #pragma unroll
;       for (int kk = 0; kk < NKK; ++kk) qf[kk] = *(const bf16x8*)(qp + kk * 16 + 8 * h); }
;     f32x16 o[NDV];
; #pragma unroll
;     for (int d = 0; d < NDV; ++d)
; #pragma unroll
;         for (int i = 0; i < 16; ++i) o[d][i] = 0.f;
;     float mrun = -INFINITY, lrun = 0.f;
;     const int lkey = tid >> 3, lq = tid & 7;
;     const bf16_t* kp0 = P.KV() + ((size_t)b * 2048 + lkey) * 2048 + hd * 256 + lq * 8;
;     const bf16_t* kp1 = P.KPE() + ((size_t)b * 2048 + lkey) * 64 + lq * 8;
;     u32x4 sreg[5];
;     ...
;     const int nsteps = 2 * (qb + 1);
;     __syncthreads();
;     MLA_LOAD(); MLA_WRITE(0);
;     MLA_LOAD();
;     __syncthreads();
;     const int kwo = (kh * 32 + r) * KSTR + h * 16;
;     const int vwo = 64 * KSTR + (kh * 32 + 4 * h + ((lane & 15) >> 2)) * VSTR + (16 * ((lane >> 4) & 1) + 4 * (lane & 3)) * 2;
;     for (int t = 0; t < nsteps; ++t) {
.LBB0_1074:
	v_mov_b32_e32 v30, v188
	s_xor_b32 s4, s16, 15
	s_lshl_b32 s19, s4, 7
	v_readfirstlane_b32 s16, v30
	s_bfe_u32 s18, s16, 0x20006
	s_lshl_b32 s14, s18, 5
	v_and_b32_e32 v31, 31, v30
	s_or_b32 s22, s14, s19
	v_or_b32_e32 v214, s22, v31
	v_or_b32_e32 v130, s50, v214
	s_waitcnt lgkmcnt(0)
	v_mov_b64_e32 v[0:1], s[10:11]
	v_mad_u64_u32 v[0:1], s[14:15], v130, s90, v[0:1]
	v_bfe_u32 v32, v30, 5, 1
	v_mad_i32_i24 v1, s51, v207, v1
	s_lshl_b32 s38, s17, 1
	v_lshl_add_u64 v[0:1], v[0:1], 0, s[38:39]
	v_lshlrev_b32_e32 v128, 4, v32
	v_lshl_add_u64 v[0:1], v[0:1], 0, v[128:129]
	global_load_dwordx4 v[180:183], v[0:1], off
	global_load_dwordx4 v[176:179], v[0:1], off offset:32
	global_load_dwordx4 v[172:175], v[0:1], off offset:64
	global_load_dwordx4 v[168:171], v[0:1], off offset:96
	global_load_dwordx4 v[164:167], v[0:1], off offset:128
	global_load_dwordx4 v[160:163], v[0:1], off offset:160
	global_load_dwordx4 v[156:159], v[0:1], off offset:192
	global_load_dwordx4 v[152:155], v[0:1], off offset:224
	global_load_dwordx4 v[148:151], v[0:1], off offset:256
	global_load_dwordx4 v[144:147], v[0:1], off offset:288
	global_load_dwordx4 v[140:143], v[0:1], off offset:320
	global_load_dwordx4 v[136:139], v[0:1], off offset:352
	v_ashrrev_i32_e32 v20, 3, v30
	v_ashrrev_i32_e32 v21, 31, v20
	v_lshl_add_u64 v[0:1], s[50:51], 0, v[20:21]
	v_lshlrev_b64 v[2:3], 12, v[0:1]
	v_lshl_add_u64 v[2:3], s[12:13], 0, v[2:3]
	s_lshl_b32 s38, s48, 1
	v_lshlrev_b32_e32 v4, 4, v30
	v_lshlrev_b64 v[0:1], 7, v[0:1]
	v_lshl_add_u64 v[2:3], v[2:3], 0, s[38:39]
	v_and_b32_e32 v116, 0x70, v4
	v_mov_b32_e32 v117, v129
	v_lshl_add_u64 v[0:1], s[42:43], 0, v[0:1]
	v_lshl_add_u64 v[22:23], v[2:3], 0, v[116:117]
	v_lshl_add_u64 v[24:25], v[0:1], 0, v[116:117]
	s_barrier
	global_load_dwordx4 v[0:3], v[24:25], off
	global_load_dwordx4 v[4:7], v[22:23], off
	global_load_dwordx4 v[8:11], v[22:23], off offset:128
	global_load_dwordx4 v[12:15], v[22:23], off offset:256
	global_load_dwordx4 v[16:19], v[22:23], off offset:384
	v_add_co_u32_e32 v26, vcc, s89, v22
	s_movk_i32 s14, 0x2000
	s_nop 0
	v_addc_co_u32_e32 v27, vcc, 0, v23, vcc
	global_load_dwordx4 v[96:99], v[26:27], off
	global_load_dwordx4 v[100:103], v[26:27], off offset:128
	global_load_dwordx4 v[104:107], v[26:27], off offset:256
	v_add_co_u32_e32 v28, vcc, s14, v24
	s_lshl_b32 s15, s4, 1
	s_nop 0
	v_addc_co_u32_e32 v29, vcc, 0, v25, vcc
	global_load_dwordx4 v[108:111], v[26:27], off offset:384
	global_load_dwordx4 v[112:115], v[28:29], off
	s_movk_i32 s4, 0x190
	v_mul_lo_u32 v117, v20, s4
	v_bfe_u32 v27, v30, 2, 2
	s_movk_i32 s36, 0x120
	v_add3_u32 v26, 0, v117, v116
	s_movk_i32 s34, 0xff90
	s_ashr_i32 s17, s16, 8
	v_mul_lo_u32 v122, v20, s36
	v_mad_u64_u32 v[20:21], s[34:35], v20, s34, v[26:27]
	v_lshlrev_b32_e32 v209, 2, v32
	s_lshl_b32 s23, s17, 5
	s_mov_b64 s[34:35], 0x4000
	v_and_b32_e32 v208, 63, v30
	v_or_b32_e32 v21, s23, v31
	v_or3_b32 v27, v209, v27, s23
	v_lshl_add_u64 v[118:119], v[24:25], 0, s[34:35]
	s_mov_b64 s[34:35], 0x80000
	v_mov_b32_e32 v31, v129
	v_mul_lo_u32 v215, v21, s4
	v_mul_lo_u32 v210, v27, s36
	v_lshl_add_u64 v[120:121], v[22:23], 0, s[34:35]
	v_mov_b32_e32 v21, v129
	v_mov_b32_e32 v22, v129
	v_mov_b32_e32 v23, v129
	v_mov_b32_e32 v24, v129
	v_mov_b32_e32 v25, v129
	v_mov_b32_e32 v27, v129
	v_mov_b32_e32 v28, v129
	v_mov_b32_e32 v29, v129
	v_mov_b32_e32 v131, s51
	s_mov_b32 s14, 0
	s_or_b32 s34, s22, 31
	s_or_b32 s35, s19, 64
	v_or_b32_e32 v123, s23, v209
	v_mov_b32_e32 v213, 0
	v_mov_b32_e32 v124, 0xff800000
	s_mov_b32 s4, 0
	s_waitcnt vmcnt(9)
	ds_write_b128 v26, v[0:3] offset:256
	s_waitcnt vmcnt(8)
	ds_write_b128 v26, v[4:7]
	s_waitcnt vmcnt(7)
	ds_write_b128 v26, v[8:11] offset:128
	s_waitcnt vmcnt(6)
	ds_write_b128 v20, v[12:15] offset:25600
	s_waitcnt vmcnt(5)
	ds_write_b128 v20, v[16:19] offset:25728
	v_and_b32_e32 v0, 16, v30
	v_lshlrev_b32_e32 v1, 2, v30
	v_mov_b32_e32 v30, v129
	v_and_or_b32 v0, v1, 12, v0
	v_mov_b32_e32 v16, v129
	v_mov_b32_e32 v17, v129
	v_mov_b32_e32 v18, v129
	v_mov_b32_e32 v19, v129
	v_mov_b32_e32 v20, v129
	v_mov_b32_e32 v26, v129
	v_mov_b64_e32 v[46:47], v[30:31]
	v_mov_b64_e32 v[62:63], v[30:31]
	v_mov_b64_e32 v[78:79], v[30:31]
	v_lshlrev_b32_e32 v211, 1, v0
	v_mov_b64_e32 v[44:45], v[28:29]
	v_mov_b64_e32 v[42:43], v[26:27]
	v_mov_b64_e32 v[40:41], v[24:25]
	v_mov_b64_e32 v[38:39], v[22:23]
	v_mov_b64_e32 v[36:37], v[20:21]
	v_mov_b64_e32 v[34:35], v[18:19]
	v_mov_b64_e32 v[32:33], v[16:17]
	v_mov_b64_e32 v[60:61], v[28:29]
	v_mov_b64_e32 v[58:59], v[26:27]
	v_mov_b64_e32 v[56:57], v[24:25]
	v_mov_b64_e32 v[54:55], v[22:23]
	v_mov_b64_e32 v[52:53], v[20:21]
	v_mov_b64_e32 v[50:51], v[18:19]
	v_mov_b64_e32 v[48:49], v[16:17]
	v_mov_b64_e32 v[76:77], v[28:29]
	v_mov_b64_e32 v[74:75], v[26:27]
	v_mov_b64_e32 v[72:73], v[24:25]
	v_mov_b64_e32 v[70:71], v[22:23]
	v_mov_b64_e32 v[68:69], v[20:21]
	v_mov_b64_e32 v[66:67], v[18:19]
	v_mov_b64_e32 v[64:65], v[16:17]
	s_waitcnt lgkmcnt(0)
	s_barrier
	s_cmp_lg_u32 s23, 0
	s_cbranch_scc0 .Lprio_skip_2
	s_setprio 1
.Lprio_skip_2:
.LBB0_1075:
	s_add_i32 s36, s4, 1
	s_bitcmp1_b32 s36, 0
	s_cselect_b32 s19, 0xac00, 0
	s_add_i32 s19, s19, 0
	v_add3_u32 v0, s19, v117, v116
	v_add3_u32 v1, s19, v122, v116
	s_cmp_ge_u32 s4, s15
	s_waitcnt vmcnt(4)
	ds_write_b128 v0, v[96:99]
	s_waitcnt vmcnt(3)
	ds_write_b128 v0, v[100:103] offset:128
	s_waitcnt vmcnt(0)
	ds_write_b128 v0, v[112:115] offset:256
	ds_write_b128 v1, v[104:107] offset:25600
	ds_write_b128 v1, v[108:111] offset:25728
	s_cbranch_scc1 .LBB0_1077
	global_load_dwordx4 v[96:99], v[120:121], off
	global_load_dwordx4 v[100:103], v[120:121], off offset:128
	global_load_dwordx4 v[104:107], v[120:121], off offset:256
	global_load_dwordx4 v[108:111], v[120:121], off offset:384
	global_load_dwordx4 v[112:115], v[118:119], off
	v_lshl_add_u64 v[120:121], v[120:121], 0, s[20:21]
	v_lshl_add_u64 v[118:119], v[118:119], 0, s[24:25]

; #define LAS __attribute__((address_space(3)))
; DI int crow(int i, int h) { return (i & 3) + 8 * (i >> 2) + 4 * h; }
; #define MFMA32(a, b, c) __builtin_amdgcn_mfma_f32_32x32x16_bf16((a), (b), (c), 0, 0, 0)
; template <bool ATOM>
; DI void mla_unit(LAS unsigned char* lds, const AttnPtrs& P, int b, int hd, int qb) {
;     ...
;         const int keyb = t * 64 + kh * 32;
;         if (keyb <= qb * 128 + rg * 32 + 31) {
;             const LAS unsigned char* Kw = lds + (t & 1) * BUFB + kwo;
;             const LAS unsigned char* Vw = lds + (t & 1) * BUFB + vwo;
;             f32x16 xa, xb;
; #pragma unroll
;             for (int i = 0; i < 16; ++i) { xa[i] = 0.f; xb[i] = 0.f; }
; #pragma unroll
;             for (int kk = 0; kk < NKK; kk += 2) {
;                 const bf16x8 a0 = *(const LAS bf16x8*)(Kw + kk * 32), a1 = *(const LAS bf16x8*)(Kw + kk * 32 + 32);
;                 xa = MFMA32(a0, qf[kk], xa); xb = MFMA32(a1, qf[kk + 1], xb);
;                 if ((kk & 3) == 2) __builtin_amdgcn_sched_barrier(0);
;             }
;             f32x16 x0;
; #pragma unroll
;             for (int i = 0; i < 16; ++i) x0[i] = xa[i] + xb[i];
;             if (keyb + 31 > qb * 128 + rg * 32) {
; #pragma unroll
;                 for (int i = 0; i < 16; ++i) if (keyb + crow(i, h) > fq_) x0[i] = -INFINITY;
;             }
;             float mloc = x0[0];
; #pragma unroll
;             for (int i = 1; i < 16; ++i) mloc = fmaxf(mloc, x0[i]);
;             mloc = fmaxf(mloc, __shfl_xor(mloc, 32));
.LBB0_1086:
	s_setprio 0
	s_lshl_b32 s4, s36, 6
	s_add_i32 s4, s4, s23
	s_cmp_le_i32 s4, s34
	s_mov_b64 s[14:15], -1
	s_cbranch_scc0 .LBB0_1092
	s_waitcnt vmcnt(2)
	v_add3_u32 v104, s19, v215, v128
	ds_read_b128 v[0:3], v104
	ds_read_b128 v[80:83], v104 offset:32
	ds_read_b128 v[96:99], v104 offset:64
	ds_read_b128 v[100:103], v104 offset:96
	s_waitcnt lgkmcnt(3)
	v_mfma_f32_32x32x16_bf16 v[0:15], v[0:3], v[180:183], 0
	s_waitcnt lgkmcnt(2)
	v_mfma_f32_32x32x16_bf16 v[80:95], v[80:83], v[176:179], 0
	s_waitcnt lgkmcnt(1)
	v_mfma_f32_32x32x16_bf16 v[0:15], v[96:99], v[172:175], v[0:15]
	s_waitcnt lgkmcnt(0)
	v_mfma_f32_32x32x16_bf16 v[80:95], v[100:103], v[168:171], v[80:95]
	ds_read_b128 v[96:99], v104 offset:128
	s_waitcnt lgkmcnt(0)
	v_mfma_f32_32x32x16_bf16 v[0:15], v[96:99], v[164:167], v[0:15]
	ds_read_b128 v[96:99], v104 offset:160
	s_waitcnt lgkmcnt(0)
	v_mfma_f32_32x32x16_bf16 v[80:95], v[96:99], v[160:163], v[80:95]
	ds_read_b128 v[96:99], v104 offset:192
	s_waitcnt lgkmcnt(0)
	v_mfma_f32_32x32x16_bf16 v[0:15], v[96:99], v[156:159], v[0:15]
	ds_read_b128 v[96:99], v104 offset:224
	s_waitcnt lgkmcnt(0)
	v_mfma_f32_32x32x16_bf16 v[80:95], v[96:99], v[152:155], v[80:95]
	ds_read_b128 v[96:99], v104 offset:256
	s_waitcnt lgkmcnt(0)
	v_mfma_f32_32x32x16_bf16 v[0:15], v[96:99], v[148:151], v[0:15]
	ds_read_b128 v[96:99], v104 offset:288
	s_waitcnt lgkmcnt(0)
	v_mfma_f32_32x32x16_bf16 v[80:95], v[96:99], v[144:147], v[80:95]
	ds_read_b128 v[96:99], v104 offset:320
	s_waitcnt lgkmcnt(0)
	v_mfma_f32_32x32x16_bf16 v[0:15], v[96:99], v[140:143], v[0:15]
	ds_read_b128 v[96:99], v104 offset:352
	s_waitcnt lgkmcnt(0)
	v_mfma_f32_32x32x16_bf16 v[80:95], v[96:99], v[136:139], v[80:95]
	s_or_b32 s14, s4, 31
	s_nop 10
	v_pk_add_f32 v[136:137], v[14:15], v[94:95]
	v_pk_add_f32 v[138:139], v[12:13], v[92:93]
	v_pk_add_f32 v[140:141], v[10:11], v[90:91]
	v_pk_add_f32 v[142:143], v[8:9], v[88:89]
	v_pk_add_f32 v[144:145], v[6:7], v[86:87]
	v_pk_add_f32 v[146:147], v[4:5], v[84:85]
	v_pk_add_f32 v[148:149], v[2:3], v[82:83]
	s_cmp_le_i32 s14, s22
	v_pk_add_f32 v[150:151], v[0:1], v[80:81]
	s_cbranch_scc1 .LBB0_1089
	v_or_b32_e32 v0, s4, v209
	v_cmp_lt_i32_e32 vcc, v0, v214
	v_or_b32_e32 v1, 2, v0
	s_nop 0
	v_cndmask_b32_e32 v151, v205, v151, vcc
	v_cmp_le_i32_e32 vcc, v0, v214
	s_nop 1
	v_cndmask_b32_e32 v150, v205, v150, vcc
	v_cmp_le_i32_e32 vcc, v1, v214
	v_or_b32_e32 v1, 3, v0
	s_nop 0
	v_cndmask_b32_e32 v148, v205, v148, vcc
	v_cmp_le_i32_e32 vcc, v1, v214
	v_or_b32_e32 v1, 8, v0
	s_nop 0
	v_cndmask_b32_e32 v149, v205, v149, vcc
	v_cmp_le_i32_e32 vcc, v1, v214
	v_or_b32_e32 v1, 9, v0
	s_nop 0
	v_cndmask_b32_e32 v146, v205, v146, vcc
	v_cmp_le_i32_e32 vcc, v1, v214
	v_or_b32_e32 v1, 10, v0
	s_nop 0
	v_cndmask_b32_e32 v147, v205, v147, vcc
	v_cmp_le_i32_e32 vcc, v1, v214
	v_or_b32_e32 v1, 11, v0
	s_nop 0
	v_cndmask_b32_e32 v144, v205, v144, vcc
	v_cmp_le_i32_e32 vcc, v1, v214
	v_or_b32_e32 v1, 16, v0
	s_nop 0
	v_cndmask_b32_e32 v145, v205, v145, vcc
	v_cmp_le_i32_e32 vcc, v1, v214
	v_or_b32_e32 v1, 17, v0
	s_nop 0
	v_cndmask_b32_e32 v142, v205, v142, vcc
	v_cmp_le_i32_e32 vcc, v1, v214
	v_or_b32_e32 v1, 18, v0
	s_nop 0
	v_cndmask_b32_e32 v143, v205, v143, vcc
	v_cmp_le_i32_e32 vcc, v1, v214
	v_or_b32_e32 v1, 19, v0
	s_nop 0
	v_cndmask_b32_e32 v140, v205, v140, vcc
	v_cmp_le_i32_e32 vcc, v1, v214
	v_or_b32_e32 v1, 24, v0
	s_nop 0
	v_cndmask_b32_e32 v141, v205, v141, vcc
	v_cmp_le_i32_e32 vcc, v1, v214
	v_or_b32_e32 v1, 25, v0
	s_nop 0
	v_cndmask_b32_e32 v138, v205, v138, vcc
	v_cmp_le_i32_e32 vcc, v1, v214
	v_or_b32_e32 v1, 26, v0
	v_or_b32_e32 v0, 27, v0
	v_cndmask_b32_e32 v139, v205, v139, vcc
	v_cmp_le_i32_e32 vcc, v1, v214
	s_nop 1
	v_cndmask_b32_e32 v136, v205, v136, vcc
	v_cmp_le_i32_e32 vcc, v0, v214
	s_nop 1
	v_cndmask_b32_e32 v137, v205, v137, vcc
